# adds the same rstd LDS-sharing to the odd-layer input-projection epilogue (EpiInOdd); bit-identical outputs
# baseline (speedup 1.0000x reference)
; #define GAS __attribute__((address_space(1)))
; template <int LD, int S0, int NS>
; __device__ __forceinline__ void rows_rstd(const float* st, int row0, int fq, float inv_n, float (&r)[2][4]) {
; #pragma unroll
;     for (int ai = 0; ai < 2; ++ai)
; #pragma unroll
;         for (int m = 0; m < 4; ++m) {
;             const GAS float* p = (const GAS float*)st + (size_t)(row0 + ai * 128 + m * 16) * LD + S0;
;             float s = 0.f;
;             if (NS == 32) { const f32x4 a = *(const GAS f32x4*)(p + fq * 8), b = *(const GAS f32x4*)(p + fq * 8 + 4); s = (a.x + a.y) + (a.z + a.w) + (b.x + b.y) + (b.z + b.w); }
;             else { if (fq * 4 < NS) { const f32x4 a = *(const GAS f32x4*)(p + fq * 4); s = (a.x + a.y) + (a.z + a.w); } }
;             s += __shfl_xor(s, 16); s += __shfl_xor(s, 32);
;             r[ai][m] = 1.0f / sqrtf(s * inv_n + EPS);
;         }
; }
;     __device__ __forceinline__ void operator()(const Acc& acc, const Unit& u, int wr, int wc, int fr, int fq) const {
;     ...
;         const int row0 = u.pm * 256 + wr * 64 + fr, colw = u.pn * 256 + wc * 32 + 8 * fq;
;         float rs[2][4]; rows_rstd<32, 0, 32>(ssq, row0, fq, 1.0f / D, rs);
.LBB0_198:
	v_mov_b32_e32 v130, v178
	v_mov_b32_e32 v131, v165
	s_lshl_b32 s4, s8, 8
	s_add_i32 s4, s4, s57
	v_cmp_lt_i32_e32 vcc, v212, v218
	v_add_u32_e32 v150, s4, v131
	s_lshl_b32 s4, s64, 8
	v_lshlrev_b32_e32 v130, 3, v130
	v_cndmask_b32_e32 v132, v207, v212, vcc
	v_cmp_lt_i32_e32 vcc, v213, v218
	s_or_b32 s4, s4, s58
	v_ashrrev_i32_e32 v131, 31, v130
	v_lshlrev_b32_e32 v182, 2, v132
	v_cndmask_b32_e32 v132, v207, v213, vcc
	v_ashrrev_i32_e32 v151, 31, v150
	v_add_u32_e32 v148, s4, v130
	v_lshl_add_u64 v[130:131], v[130:131], 2, s[68:69]
	v_lshlrev_b32_e32 v149, 2, v132
	v_lshlrev_b64 v[132:133], 7, v[150:151]
	v_lshl_add_u64 v[136:137], v[130:131], 0, v[132:133]
	s_lshr_b32 s4, s58, 5
	s_and_b32 s5, s4, 1
	s_lshl_b32 s5, s5, 12
	s_lshr_b32 s4, s4, 1
	s_lshl_b32 s4, s4, 14
	s_add_i32 s4, s4, s5
	s_mov_b32 s5, 0
	v_lshl_add_u64 v[224:225], v[136:137], 0, s[4:5]
	global_load_dwordx4 v[132:135], v[224:225], off offset:16
	global_load_dwordx4 v[166:169], v[224:225], off
	global_load_dwordx4 v[228:231], v[224:225], off offset:2064
	global_load_dwordx4 v[232:235], v[224:225], off offset:2048
	s_waitcnt vmcnt(2)
	v_add_f32_e32 v136, v166, v167
	v_add_f32_e32 v137, v168, v169
	v_add_f32_e32 v152, v136, v137
	v_mov_b32_e32 v136, v134
	v_mov_b32_e32 v137, v132
	v_mov_b32_e32 v132, v135
	v_pk_add_f32 v[132:133], v[136:137], v[132:133]
	s_nop 0
	v_add_f32_e32 v133, v152, v133
	v_add_f32_e32 v132, v132, v133
	ds_bpermute_b32 v133, v182, v132
	s_waitcnt lgkmcnt(0)
	v_add_f32_e32 v132, v132, v133
	ds_bpermute_b32 v133, v149, v132
	s_waitcnt lgkmcnt(0)
	v_add_f32_e32 v132, v132, v133
	v_fmamk_f32 v132, v132, 0x3a000000, v205
	v_cmp_gt_f32_e32 vcc, s16, v132
	v_mul_f32_e32 v133, 0x4f800000, v132
	s_nop 0
	v_cndmask_b32_e32 v132, v132, v133, vcc
	v_sqrt_f32_e32 v133, v132
	s_nop 0
	v_add_u32_e32 v134, -1, v133
	v_fma_f32 v135, -v134, v133, v132
	v_cmp_ge_f32_e64 s[8:9], 0, v135
	v_add_u32_e32 v135, 1, v133
	s_nop 0
	v_cndmask_b32_e64 v134, v133, v134, s[8:9]
	v_fma_f32 v133, -v135, v133, v132
	v_cmp_lt_f32_e64 s[8:9], 0, v133
	s_nop 1
	v_cndmask_b32_e64 v133, v134, v135, s[8:9]
	v_mul_f32_e32 v134, 0x37800000, v133
	v_cndmask_b32_e32 v133, v133, v134, vcc
	v_cmp_class_f32_e32 vcc, v132, v206
	s_nop 1
	v_cndmask_b32_e32 v132, v133, v132, vcc
	v_div_scale_f32 v133, s[4:5], v132, v132, 1.0
	v_rcp_f32_e32 v134, v133
	s_nop 0
	v_fma_f32 v135, -v133, v134, 1.0
	v_fmac_f32_e32 v134, v135, v134
	v_div_scale_f32 v135, vcc, 1.0, v132, 1.0
	v_mul_f32_e32 v136, v135, v134
	v_fma_f32 v137, -v133, v136, v135
	v_fmac_f32_e32 v136, v137, v134
	v_fma_f32 v133, -v133, v136, v135
	v_div_fmas_f32 v133, v133, v134, v136
	v_div_fixup_f32 v236, v133, v132, 1.0
	s_waitcnt vmcnt(0)
	v_mov_b32_e32 v132, v228
	v_mov_b32_e32 v133, v229
	v_mov_b32_e32 v134, v230
	v_mov_b32_e32 v135, v231
	v_mov_b32_e32 v166, v232
	v_mov_b32_e32 v167, v233
	v_mov_b32_e32 v168, v234
	v_mov_b32_e32 v169, v235
	v_add_f32_e32 v136, v166, v167
	v_add_f32_e32 v137, v168, v169
	v_add_f32_e32 v152, v136, v137
	v_mov_b32_e32 v136, v134
	v_mov_b32_e32 v137, v132
	v_mov_b32_e32 v132, v135
	v_pk_add_f32 v[132:133], v[136:137], v[132:133]
	s_nop 0
	v_add_f32_e32 v133, v152, v133
	v_add_f32_e32 v132, v132, v133
	ds_bpermute_b32 v133, v182, v132
	s_waitcnt lgkmcnt(0)
	v_add_f32_e32 v132, v132, v133
	ds_bpermute_b32 v133, v149, v132
	s_waitcnt lgkmcnt(0)
	v_add_f32_e32 v132, v132, v133
	v_fmamk_f32 v132, v132, 0x3a000000, v205
	v_cmp_gt_f32_e32 vcc, s16, v132
	v_mul_f32_e32 v133, 0x4f800000, v132
	s_nop 0
	v_cndmask_b32_e32 v132, v132, v133, vcc
	v_sqrt_f32_e32 v133, v132
	s_nop 0
	v_add_u32_e32 v134, -1, v133
	v_fma_f32 v135, -v134, v133, v132
	v_cmp_ge_f32_e64 s[8:9], 0, v135
	v_add_u32_e32 v135, 1, v133
	s_nop 0
	v_cndmask_b32_e64 v134, v133, v134, s[8:9]
	v_fma_f32 v133, -v135, v133, v132
	v_cmp_lt_f32_e64 s[8:9], 0, v133
	s_nop 1
	v_cndmask_b32_e64 v133, v134, v135, s[8:9]
	v_mul_f32_e32 v134, 0x37800000, v133
	v_cndmask_b32_e32 v133, v133, v134, vcc
	v_cmp_class_f32_e32 vcc, v132, v206
	s_nop 1
	v_cndmask_b32_e32 v132, v133, v132, vcc
	v_div_scale_f32 v133, s[4:5], v132, v132, 1.0
	v_rcp_f32_e32 v134, v133
	s_nop 0
	v_fma_f32 v135, -v133, v134, 1.0
	v_fmac_f32_e32 v134, v135, v134
	v_div_scale_f32 v135, vcc, 1.0, v132, 1.0
	v_mul_f32_e32 v136, v135, v134
	v_fma_f32 v137, -v133, v136, v135
	v_fmac_f32_e32 v136, v137, v134
	v_fma_f32 v133, -v133, v136, v135
	v_div_fmas_f32 v133, v133, v134, v136
	v_div_fixup_f32 v237, v133, v132, 1.0
	s_lshl_b32 s4, s57, 3
	s_lshl_b32 s5, s58, 2
	s_add_i32 s4, s4, 139392
	s_add_i32 s5, s5, s4
	v_lshl_add_u32 v238, v165, 2, s5
	v_lshl_add_u32 v239, v165, 2, s4
	ds_write_b32 v238, v236
	ds_write_b32 v238, v237 offset:64
	s_waitcnt lgkmcnt(0)
	s_barrier
; #define GAS __attribute__((address_space(1)))
; __device__ __forceinline__ u32x4 pack8(const float* v) { u32x4 w; w.x = cvt_pk_bf16(v[0], v[1]); w.y = cvt_pk_bf16(v[2], v[3]); w.z = cvt_pk_bf16(v[4], v[5]); w.w = cvt_pk_bf16(v[6], v[7]); return w; }
; template <int LD, int S0, int NS>
; __device__ __forceinline__ void rows_rstd(const float* st, int row0, int fq, float inv_n, float (&r)[2][4]) {
; #pragma unroll
;     for (int ai = 0; ai < 2; ++ai)
; #pragma unroll
;         for (int m = 0; m < 4; ++m) {
;             const GAS float* p = (const GAS float*)st + (size_t)(row0 + ai * 128 + m * 16) * LD + S0;
;             float s = 0.f;
;             if (NS == 32) { const f32x4 a = *(const GAS f32x4*)(p + fq * 8), b = *(const GAS f32x4*)(p + fq * 8 + 4); s = (a.x + a.y) + (a.z + a.w) + (b.x + b.y) + (b.z + b.w); }
;             else { if (fq * 4 < NS) { const f32x4 a = *(const GAS f32x4*)(p + fq * 4); s = (a.x + a.y) + (a.z + a.w); } }
;             s += __shfl_xor(s, 16); s += __shfl_xor(s, 32);
;             r[ai][m] = 1.0f / sqrtf(s * inv_n + EPS);
;         }
; }
;     __device__ __forceinline__ void operator()(const Acc& acc, const Unit& u, int wr, int wc, int fr, int fq) const {
;     ...
;         const int row0 = u.pm * 256 + wr * 64 + fr, colw = u.pn * 256 + wc * 32 + 8 * fq;
;         float rs[2][4]; rows_rstd<32, 0, 32>(ssq, row0, fq, 1.0f / D, rs);
;         const float qs = (u.pn == 2 || u.pn == 3) ? QSCALE_D : 1.0f;
; #pragma unroll
;         for (int ai = 0; ai < 2; ++ai)
; #pragma unroll
;             for (int m = 0; m < 4; ++m) { const int row = row0 + ai * 128 + m * 16; const float r = rs[ai][m] * qs;
; #pragma unroll
;                 for (int bj = 0; bj < 2; ++bj) { float o[8];
; #pragma unroll
;                     for (int n = 0; n < 2; ++n)
; #pragma unroll
;                         for (int j = 0; j < 4; ++j) o[4 * n + j] = acc[ai][bj][m][n][j] * r;
;                     *(GAS u32x4*)((GAS bf16_t*)proj + (size_t)row * INO + colw + bj * 128) = pack8(o); } __builtin_amdgcn_sched_barrier(0); }
	ds_read_b32 v181, v239
	ds_read_b32 v183, v239 offset:64
	ds_read_b32 v184, v239 offset:128
	ds_read_b32 v185, v239 offset:192
	ds_read_b32 v186, v239 offset:256
	ds_read_b32 v187, v239 offset:320
	ds_read_b32 v188, v239 offset:384
	ds_read_b32 v132, v239 offset:448
	v_add_u32_e32 v152, 16, v150
	v_ashrrev_i32_e32 v153, 31, v152
	v_add_u32_e32 v166, 32, v150
	v_ashrrev_i32_e32 v167, 31, v166
	v_add_u32_e32 v168, 48, v150
	v_ashrrev_i32_e32 v169, 31, v168
	v_add_u32_e32 v170, 0x80, v150
	v_ashrrev_i32_e32 v171, 31, v170
	v_add_u32_e32 v172, 0x90, v150
	v_ashrrev_i32_e32 v173, 31, v172
	v_add_u32_e32 v174, 0xa0, v150
	v_ashrrev_i32_e32 v175, 31, v174
	v_add_u32_e32 v176, 0xb0, v150
	v_ashrrev_i32_e32 v177, 31, v176
	v_ashrrev_i32_e32 v149, 31, v148
	s_waitcnt lgkmcnt(0)
	s_and_b32 s4, s64, -2
	s_cmp_eq_u32 s4, 2
	s_cselect_b64 vcc, -1, 0
	v_cndmask_b32_e32 v133, 1.0, v217, vcc
	v_mul_f32_e32 v134, v133, v181
	v_lshlrev_b64 v[130:131], 12, v[150:151]
	v_mul_f32_e32 v126, v126, v134
	v_mul_f32_e32 v128, v128, v134
	v_mul_f32_e32 v129, v129, v134
	v_mul_f32_e32 v122, v122, v134
	v_mul_f32_e32 v123, v123, v134
	v_mul_f32_e32 v127, v127, v134
	v_mul_f32_e32 v135, v124, v134
	v_mul_f32_e32 v136, v125, v134
	v_cvt_pk_bf16_f32 v124, v126, v127
	v_cvt_pk_bf16_f32 v125, v128, v129
	v_cvt_pk_bf16_f32 v126, v122, v123
	v_lshl_add_u64 v[128:129], s[40:41], 0, v[130:131]
	v_lshlrev_b64 v[122:123], 1, v[148:149]
	v_lshl_add_u64 v[128:129], v[128:129], 0, v[122:123]
	v_mul_f32_e32 v117, v117, v134
	v_cvt_pk_bf16_f32 v127, v135, v136
	global_store_dwordx4 v[128:129], v[124:127], off
	v_mul_f32_e32 v118, v118, v134
	v_mul_f32_e32 v119, v119, v134
	v_mul_f32_e32 v120, v120, v134
	v_mul_f32_e32 v121, v121, v134
	v_mul_f32_e32 v124, v114, v134
	v_mul_f32_e32 v125, v115, v134
	v_mul_f32_e32 v126, v116, v134
	v_cvt_pk_bf16_f32 v114, v118, v119
	v_cvt_pk_bf16_f32 v115, v120, v121
	v_cvt_pk_bf16_f32 v116, v124, v125
	v_cvt_pk_bf16_f32 v117, v126, v117
	global_store_dwordx4 v[128:129], v[114:117], off offset:256
	s_nop 1
	v_mul_f32_e32 v116, v133, v183
	v_lshlrev_b64 v[114:115], 12, v[152:153]
	v_mul_f32_e32 v110, v110, v116
	v_mul_f32_e32 v111, v111, v116
	v_mul_f32_e32 v117, v106, v116
	v_cvt_pk_bf16_f32 v106, v110, v111
	v_lshl_add_u64 v[110:111], s[40:41], 0, v[114:115]
	v_mul_f32_e32 v112, v112, v116
	v_mul_f32_e32 v113, v113, v116
	v_mul_f32_e32 v118, v107, v116
	v_mul_f32_e32 v119, v108, v116
	v_mul_f32_e32 v109, v109, v116
	v_cvt_pk_bf16_f32 v107, v112, v113
	v_cvt_pk_bf16_f32 v108, v117, v118
	v_lshl_add_u64 v[110:111], v[110:111], 0, v[122:123]
	v_mul_f32_e32 v101, v101, v116
	v_cvt_pk_bf16_f32 v109, v119, v109
	global_store_dwordx4 v[110:111], v[106:109], off
	v_mul_f32_e32 v102, v102, v116
	v_mul_f32_e32 v103, v103, v116
	v_mul_f32_e32 v104, v104, v116
	v_mul_f32_e32 v105, v105, v116
	v_mul_f32_e32 v106, v98, v116
	v_mul_f32_e32 v107, v99, v116
	v_mul_f32_e32 v108, v100, v116
	v_cvt_pk_bf16_f32 v98, v102, v103
	v_cvt_pk_bf16_f32 v99, v104, v105
	v_cvt_pk_bf16_f32 v100, v106, v107
	v_cvt_pk_bf16_f32 v101, v108, v101
	global_store_dwordx4 v[110:111], v[98:101], off offset:256
	s_nop 1
	v_mul_f32_e32 v100, v133, v184
	v_lshlrev_b64 v[98:99], 12, v[166:167]
	v_mul_f32_e32 v94, v94, v100
	v_mul_f32_e32 v95, v95, v100
	v_mul_f32_e32 v101, v90, v100
	v_cvt_pk_bf16_f32 v90, v94, v95
	v_lshl_add_u64 v[94:95], s[40:41], 0, v[98:99]
	v_mul_f32_e32 v96, v96, v100
	v_mul_f32_e32 v97, v97, v100
	v_mul_f32_e32 v102, v91, v100
	v_mul_f32_e32 v103, v92, v100
	v_mul_f32_e32 v93, v93, v100
	v_cvt_pk_bf16_f32 v91, v96, v97
	v_cvt_pk_bf16_f32 v92, v101, v102
	v_lshl_add_u64 v[94:95], v[94:95], 0, v[122:123]
	v_mul_f32_e32 v85, v85, v100
	v_cvt_pk_bf16_f32 v93, v103, v93
	global_store_dwordx4 v[94:95], v[90:93], off
	v_mul_f32_e32 v86, v86, v100
	v_mul_f32_e32 v87, v87, v100
	v_mul_f32_e32 v88, v88, v100
	v_mul_f32_e32 v89, v89, v100
	v_mul_f32_e32 v90, v82, v100
	v_mul_f32_e32 v91, v83, v100
	v_mul_f32_e32 v92, v84, v100
	v_cvt_pk_bf16_f32 v82, v86, v87
	v_cvt_pk_bf16_f32 v83, v88, v89
	v_cvt_pk_bf16_f32 v84, v90, v91
	v_cvt_pk_bf16_f32 v85, v92, v85
	global_store_dwordx4 v[94:95], v[82:85], off offset:256
	s_nop 1
	v_mul_f32_e32 v84, v133, v185
	v_lshlrev_b64 v[82:83], 12, v[168:169]
	v_mul_f32_e32 v78, v78, v84
	v_mul_f32_e32 v79, v79, v84
	v_mul_f32_e32 v85, v74, v84
	v_cvt_pk_bf16_f32 v74, v78, v79
	v_lshl_add_u64 v[78:79], s[40:41], 0, v[82:83]
	v_mul_f32_e32 v80, v80, v84
	v_mul_f32_e32 v81, v81, v84
	v_mul_f32_e32 v86, v75, v84
	v_mul_f32_e32 v87, v76, v84
	v_mul_f32_e32 v77, v77, v84
	v_cvt_pk_bf16_f32 v75, v80, v81
	v_cvt_pk_bf16_f32 v76, v85, v86
	v_lshl_add_u64 v[78:79], v[78:79], 0, v[122:123]
; #define GAS __attribute__((address_space(1)))
; __device__ __forceinline__ u32x4 pack8(const float* v) { u32x4 w; w.x = cvt_pk_bf16(v[0], v[1]); w.y = cvt_pk_bf16(v[2], v[3]); w.z = cvt_pk_bf16(v[4], v[5]); w.w = cvt_pk_bf16(v[6], v[7]); return w; }
; #define PG8_BAR __builtin_amdgcn_s_barrier()
; template <class Epi>
; __device__ __forceinline__ void gemm_phase(LAS unsigned char* lds, const Gemm g, const StaticOrder& S, const Epi& E) {
;     ...
;         if (!has_next) break;
; #pragma unroll
;         for (int a = 0; a < 2; ++a)
; #pragma unroll
;             for (int b = 0; b < 2; ++b)
; #pragma unroll
;                 for (int m = 0; m < 4; ++m)
; #pragma unroll
;                     for (int n = 0; n < 2; ++n) acc[a][b][m][n] = (f32x4){0.f, 0.f, 0.f, 0.f};
;         cur = nxt; cA = nA; cB = nB; ++ui;
;         if (wr == 1) PG8_BAR;
;     __device__ __forceinline__ void operator()(const Acc& acc, const Unit& u, int wr, int wc, int fr, int fq) const {
;     ...
;         for (int ai = 0; ai < 2; ++ai)
; #pragma unroll
;             for (int m = 0; m < 4; ++m) { const int row = row0 + ai * 128 + m * 16; const float r = rs[ai][m] * qs;
; #pragma unroll
;                 for (int bj = 0; bj < 2; ++bj) { float o[8];
; #pragma unroll
;                     for (int n = 0; n < 2; ++n)
; #pragma unroll
;                         for (int j = 0; j < 4; ++j) o[4 * n + j] = acc[ai][bj][m][n][j] * r;
;                     *(GAS u32x4*)((GAS bf16_t*)proj + (size_t)row * INO + colw + bj * 128) = pack8(o); } __builtin_amdgcn_sched_barrier(0); }
	v_mul_f32_e32 v69, v69, v84
	v_cvt_pk_bf16_f32 v77, v87, v77
	global_store_dwordx4 v[78:79], v[74:77], off
	v_mul_f32_e32 v70, v70, v84
	v_mul_f32_e32 v71, v71, v84
	v_mul_f32_e32 v72, v72, v84
	v_mul_f32_e32 v73, v73, v84
	v_mul_f32_e32 v74, v66, v84
	v_mul_f32_e32 v75, v67, v84
	v_mul_f32_e32 v76, v68, v84
	v_cvt_pk_bf16_f32 v66, v70, v71
	v_cvt_pk_bf16_f32 v67, v72, v73
	v_cvt_pk_bf16_f32 v68, v74, v75
	v_cvt_pk_bf16_f32 v69, v76, v69
	global_store_dwordx4 v[78:79], v[66:69], off offset:256
	s_nop 1
	v_mul_f32_e32 v68, v133, v186
	v_lshlrev_b64 v[66:67], 12, v[170:171]
	v_mul_f32_e32 v62, v62, v68
	v_mul_f32_e32 v63, v63, v68
	v_mul_f32_e32 v69, v58, v68
	v_cvt_pk_bf16_f32 v58, v62, v63
	v_lshl_add_u64 v[62:63], s[40:41], 0, v[66:67]
	v_mul_f32_e32 v64, v64, v68
	v_mul_f32_e32 v65, v65, v68
	v_mul_f32_e32 v70, v59, v68
	v_mul_f32_e32 v71, v60, v68
	v_mul_f32_e32 v61, v61, v68
	v_cvt_pk_bf16_f32 v59, v64, v65
	v_cvt_pk_bf16_f32 v60, v69, v70
	v_lshl_add_u64 v[62:63], v[62:63], 0, v[122:123]
	v_mul_f32_e32 v53, v53, v68
	v_cvt_pk_bf16_f32 v61, v71, v61
	global_store_dwordx4 v[62:63], v[58:61], off
	v_mul_f32_e32 v54, v54, v68
	v_mul_f32_e32 v55, v55, v68
	v_mul_f32_e32 v56, v56, v68
	v_mul_f32_e32 v57, v57, v68
	v_mul_f32_e32 v58, v50, v68
	v_mul_f32_e32 v59, v51, v68
	v_mul_f32_e32 v60, v52, v68
	v_cvt_pk_bf16_f32 v50, v54, v55
	v_cvt_pk_bf16_f32 v51, v56, v57
	v_cvt_pk_bf16_f32 v52, v58, v59
	v_cvt_pk_bf16_f32 v53, v60, v53
	global_store_dwordx4 v[62:63], v[50:53], off offset:256
	s_nop 1
	v_mul_f32_e32 v52, v133, v187
	v_lshlrev_b64 v[50:51], 12, v[172:173]
	v_mul_f32_e32 v46, v46, v52
	v_mul_f32_e32 v47, v47, v52
	v_mul_f32_e32 v53, v42, v52
	v_cvt_pk_bf16_f32 v42, v46, v47
	v_lshl_add_u64 v[46:47], s[40:41], 0, v[50:51]
	v_mul_f32_e32 v48, v48, v52
	v_mul_f32_e32 v49, v49, v52
	v_mul_f32_e32 v54, v43, v52
	v_mul_f32_e32 v55, v44, v52
	v_mul_f32_e32 v45, v45, v52
	v_cvt_pk_bf16_f32 v43, v48, v49
	v_cvt_pk_bf16_f32 v44, v53, v54
	v_lshl_add_u64 v[46:47], v[46:47], 0, v[122:123]
	v_mul_f32_e32 v37, v37, v52
	v_cvt_pk_bf16_f32 v45, v55, v45
	global_store_dwordx4 v[46:47], v[42:45], off
	v_mul_f32_e32 v38, v38, v52
	v_mul_f32_e32 v39, v39, v52
	v_mul_f32_e32 v40, v40, v52
	v_mul_f32_e32 v41, v41, v52
	v_mul_f32_e32 v42, v34, v52
	v_mul_f32_e32 v43, v35, v52
	v_mul_f32_e32 v44, v36, v52
	v_cvt_pk_bf16_f32 v34, v38, v39
	v_cvt_pk_bf16_f32 v35, v40, v41
	v_cvt_pk_bf16_f32 v36, v42, v43
	v_cvt_pk_bf16_f32 v37, v44, v37
	global_store_dwordx4 v[46:47], v[34:37], off offset:256
	s_nop 1
	v_mul_f32_e32 v36, v133, v188
	v_lshlrev_b64 v[34:35], 12, v[174:175]
	v_mul_f32_e32 v30, v30, v36
	v_mul_f32_e32 v31, v31, v36
	v_mul_f32_e32 v37, v26, v36
	v_cvt_pk_bf16_f32 v26, v30, v31
	v_lshl_add_u64 v[30:31], s[40:41], 0, v[34:35]
	v_mul_f32_e32 v32, v32, v36
	v_mul_f32_e32 v33, v33, v36
	v_mul_f32_e32 v38, v27, v36
	v_mul_f32_e32 v39, v28, v36
	v_mul_f32_e32 v29, v29, v36
	v_cvt_pk_bf16_f32 v27, v32, v33
	v_cvt_pk_bf16_f32 v28, v37, v38
	v_lshl_add_u64 v[30:31], v[30:31], 0, v[122:123]
	v_mul_f32_e32 v21, v21, v36
	v_cvt_pk_bf16_f32 v29, v39, v29
	global_store_dwordx4 v[30:31], v[26:29], off
	v_mul_f32_e32 v22, v22, v36
	v_mul_f32_e32 v23, v23, v36
	v_mul_f32_e32 v24, v24, v36
	v_mul_f32_e32 v25, v25, v36
	v_mul_f32_e32 v26, v18, v36
	v_mul_f32_e32 v27, v19, v36
	v_mul_f32_e32 v28, v20, v36
	v_cvt_pk_bf16_f32 v18, v22, v23
	v_cvt_pk_bf16_f32 v19, v24, v25
	v_cvt_pk_bf16_f32 v20, v26, v27
	v_cvt_pk_bf16_f32 v21, v28, v21
	global_store_dwordx4 v[30:31], v[18:21], off offset:256
	s_nop 1
	v_mul_f32_e32 v20, v133, v132
	v_lshlrev_b64 v[18:19], 12, v[176:177]
	v_mul_f32_e32 v14, v14, v20
	v_mul_f32_e32 v15, v15, v20
	v_mul_f32_e32 v21, v10, v20
	v_cvt_pk_bf16_f32 v10, v14, v15
	v_lshl_add_u64 v[14:15], s[40:41], 0, v[18:19]
	v_mul_f32_e32 v16, v16, v20
	v_mul_f32_e32 v17, v17, v20
	v_mul_f32_e32 v22, v11, v20
	v_mul_f32_e32 v23, v12, v20
	v_mul_f32_e32 v13, v13, v20
	v_cvt_pk_bf16_f32 v11, v16, v17
	v_cvt_pk_bf16_f32 v12, v21, v22
	v_lshl_add_u64 v[14:15], v[14:15], 0, v[122:123]
	v_mul_f32_e32 v5, v5, v20
	v_cvt_pk_bf16_f32 v13, v23, v13
	global_store_dwordx4 v[14:15], v[10:13], off
	v_mul_f32_e32 v6, v6, v20
	v_mul_f32_e32 v7, v7, v20
	v_mul_f32_e32 v8, v8, v20
	v_mul_f32_e32 v9, v9, v20
	v_mul_f32_e32 v10, v2, v20
	v_mul_f32_e32 v11, v3, v20
	v_mul_f32_e32 v12, v4, v20
	v_cvt_pk_bf16_f32 v2, v6, v7
	v_cvt_pk_bf16_f32 v3, v8, v9
	v_cvt_pk_bf16_f32 v4, v10, v11
	v_cvt_pk_bf16_f32 v5, v12, v5
	global_store_dwordx4 v[14:15], v[2:5], off offset:256
	s_andn2_b64 vcc, exec, s[6:7]
	s_mov_b64 s[4:5], -1
	s_cbranch_vccnz .LBB0_185
	s_andn2_b64 vcc, exec, s[10:11]
	s_cbranch_vccnz .LBB0_184
	s_barrier
	s_branch .LBB0_184
